# prep_rs before G5 pipelined the same way (all rounds' loads first, one wait, then reductions)
# speedup vs baseline: 1.0203x; 1.0031x over previous
.LBB0_920:
	s_or_b64 exec, exec, s[6:7]
	s_cmpk_lt_i32 s2, 0x300
	s_cselect_b64 s[4:5], -1, 0
	v_cndmask_b32_e64 v1, 0, 1, s[4:5]
	v_cmp_gt_i32_e32 vcc, s3, v0
	v_cmp_ne_u32_e64 s[44:45], 1, v1
	s_and_saveexec_b64 s[6:7], vcc
	s_cbranch_execz .LBB0_929
	s_waitcnt vmcnt(0)
	s_add_i32 s3, 0, 0x20000
	s_and_b64 vcc, exec, s[44:45]
	v_lshl_add_u32 v1, v0, 2, s3
	s_cbranch_vccnz .Lprs5_p1
	v_readlane_b32 s4, v240, 29
	v_readlane_b32 s5, v240, 30
	s_movk_i32 s3, 0x61
	s_and_b64 s[4:5], s[4:5], exec
	s_cselect_b32 s3, s3, 0x60
	v_readlane_b32 s4, v240, 32
	s_mul_i32 s3, s4, s3
	s_add_i32 s3, s3, s87
	s_mul_hi_i32 s4, s3, 0x2aaaaaab
	s_lshr_b32 s5, s4, 31
	s_ashr_i32 s4, s4, 4
	s_add_i32 s4, s4, s5
	s_mul_i32 s5, s4, 0x60
	s_sub_i32 s3, s3, s5
	s_bfe_i32 s5, s3, 0x80000
	s_bfe_u32 s5, s5, 0x3000c
	s_add_i32 s5, s3, s5
	s_and_b32 s5, s5, 0xf8
	s_sub_i32 s3, s3, s5
	s_sext_i32_i8 s3, s3
	s_lshl_b32 s4, s4, 11
	s_lshl_b32 s3, s3, 8
	s_add_i32 s3, s3, s4
	v_add_u32_e32 v26, s3, v0
	v_ashrrev_i32_e32 v27, 31, v26
	v_lshlrev_b64 v[26:27], 6, v[26:27]
	v_lshl_add_u64 v[38:39], s[0:1], 0, v[26:27]
	global_load_dwordx4 v[26:29], v[38:39], off offset:48
	global_load_dwordx4 v[30:33], v[38:39], off offset:32
	global_load_dwordx4 v[34:37], v[38:39], off offset:16
	s_nop 0
	global_load_dwordx4 v[38:41], v[38:39], off
.Lprs5_p1:
	v_readlane_b32 s4, v240, 43
	v_mov_b64_e32 v[2:3], 0x2ff
	v_readlane_b32 s5, v240, 44
	s_nop 1
	v_cmp_gt_i64_e32 vcc, s[4:5], v[2:3]
	s_cbranch_vccnz .Lprs5_p2
	v_readlane_b32 s4, v240, 38
	v_readlane_b32 s5, v240, 39
	s_movk_i32 s3, 0x61
	s_and_b64 s[4:5], s[4:5], exec
	s_cselect_b32 s3, s3, 0x60
	v_readlane_b32 s4, v240, 41
	s_mul_i32 s3, s4, s3
	v_readlane_b32 s4, v240, 37
	s_add_i32 s3, s3, s4
	s_mul_hi_i32 s4, s3, 0x2aaaaaab
	s_lshr_b32 s5, s4, 31
	s_ashr_i32 s4, s4, 4
	s_add_i32 s4, s4, s5
	s_mul_i32 s5, s4, 0x60
	s_lshl_b32 s4, s4, 3
	s_sub_i32 s3, s3, s5
	s_sub_i32 s5, 64, s4
	s_min_i32 s5, s5, 8
	s_abs_i32 s5, s5
	v_cvt_f32_u32_e32 v52, s5
	s_sub_i32 s9, 0, s5
	s_ashr_i32 s8, s3, 31
	s_abs_i32 s3, s3
	v_rcp_iflag_f32_e32 v52, v52
	s_nop 0
	v_mul_f32_e32 v52, 0x4f7ffffe, v52
	v_cvt_u32_f32_e32 v52, v52
	s_nop 0
	v_readfirstlane_b32 s10, v52
	s_mul_i32 s9, s9, s10
	s_mul_hi_u32 s9, s10, s9
	s_add_i32 s10, s10, s9
	s_mul_hi_u32 s9, s3, s10
	s_mul_i32 s9, s9, s5
	s_sub_i32 s3, s3, s9
	s_sub_i32 s9, s3, s5
	s_cmp_ge_u32 s3, s5
	s_cselect_b32 s3, s9, s3
	s_sub_i32 s9, s3, s5
	s_cmp_ge_u32 s3, s5
	s_cselect_b32 s3, s9, s3
	s_xor_b32 s3, s3, s8
	s_sub_i32 s3, s3, s8
	s_add_i32 s4, s4, s3
	v_lshl_add_u32 v52, s4, 8, v0
	v_ashrrev_i32_e32 v53, 31, v52
	v_lshlrev_b64 v[52:53], 6, v[52:53]
	v_lshl_add_u64 v[64:65], s[0:1], 0, v[52:53]
	global_load_dwordx4 v[52:55], v[64:65], off offset:48
	global_load_dwordx4 v[56:59], v[64:65], off offset:32
	global_load_dwordx4 v[60:63], v[64:65], off offset:16
	s_nop 0
	global_load_dwordx4 v[64:67], v[64:65], off
.Lprs5_p2:
	v_readlane_b32 s4, v240, 53
	v_readlane_b32 s5, v240, 54
	s_nop 1
	v_cmp_gt_i64_e32 vcc, s[4:5], v[2:3]
	s_cbranch_vccnz .Lprs5_p3
	v_readlane_b32 s4, v240, 48
	v_readlane_b32 s5, v240, 49
	s_movk_i32 s3, 0x61
	s_and_b64 s[4:5], s[4:5], exec
	s_cselect_b32 s3, s3, 0x60
	v_readlane_b32 s4, v240, 51
	s_mul_i32 s3, s4, s3
	v_readlane_b32 s4, v240, 47
	s_add_i32 s3, s3, s4
	s_mul_hi_i32 s4, s3, 0x2aaaaaab
	s_lshr_b32 s5, s4, 31
	s_ashr_i32 s4, s4, 4
	s_add_i32 s4, s4, s5
	s_mul_i32 s5, s4, 0x60
	s_lshl_b32 s4, s4, 3
	s_sub_i32 s3, s3, s5
	s_sub_i32 s5, 64, s4
	s_min_i32 s5, s5, 8
	s_abs_i32 s5, s5
	v_cvt_f32_u32_e32 v74, s5
	s_sub_i32 s9, 0, s5
	s_ashr_i32 s8, s3, 31
	s_abs_i32 s3, s3
	v_rcp_iflag_f32_e32 v74, v74
	s_nop 0
	v_mul_f32_e32 v74, 0x4f7ffffe, v74
	v_cvt_u32_f32_e32 v74, v74
	s_nop 0
	v_readfirstlane_b32 s10, v74
	s_mul_i32 s9, s9, s10
	s_mul_hi_u32 s9, s10, s9
	s_add_i32 s10, s10, s9
	s_mul_hi_u32 s9, s3, s10
	s_mul_i32 s9, s9, s5
	s_sub_i32 s3, s3, s9
	s_sub_i32 s9, s3, s5
	s_cmp_ge_u32 s3, s5
	s_cselect_b32 s3, s9, s3
	s_sub_i32 s9, s3, s5
	s_cmp_ge_u32 s3, s5
	s_cselect_b32 s3, s9, s3
	s_xor_b32 s3, s3, s8
	s_sub_i32 s3, s3, s8
	s_add_i32 s4, s4, s3
	v_lshl_add_u32 v74, s4, 8, v0
	v_ashrrev_i32_e32 v75, 31, v74
	v_lshlrev_b64 v[74:75], 6, v[74:75]
	v_lshl_add_u64 v[86:87], s[0:1], 0, v[74:75]
	global_load_dwordx4 v[74:77], v[86:87], off offset:48
	global_load_dwordx4 v[78:81], v[86:87], off offset:32
	global_load_dwordx4 v[82:85], v[86:87], off offset:16
	s_nop 0
	global_load_dwordx4 v[86:89], v[86:87], off
.Lprs5_p3:
	v_readlane_b32 s4, v240, 58
	v_mov_b64_e32 v[2:3], 0x2ff
	v_readlane_b32 s5, v240, 59
	s_nop 1
	v_cmp_gt_i64_e32 vcc, s[4:5], v[2:3]
	s_cbranch_vccnz .Lprs5_w
	v_readlane_b32 s4, v240, 60
	v_readlane_b32 s5, v240, 61
	s_movk_i32 s3, 0x61
	s_and_b64 s[4:5], s[4:5], exec
	s_cselect_b32 s3, s3, 0x60
	v_readlane_b32 s4, v240, 63
	s_mul_i32 s3, s4, s3
	v_readlane_b32 s4, v240, 57
	s_add_i32 s3, s3, s4
	s_mul_hi_i32 s4, s3, 0x2aaaaaab
	s_lshr_b32 s5, s4, 31
	s_ashr_i32 s4, s4, 4
	s_add_i32 s4, s4, s5
	s_mul_i32 s5, s4, 0x60
	s_lshl_b32 s4, s4, 3
	s_sub_i32 s3, s3, s5
	s_sub_i32 s5, 64, s4
	s_min_i32 s5, s5, 8
	s_abs_i32 s5, s5
	v_cvt_f32_u32_e32 v98, s5
	s_sub_i32 s9, 0, s5
	s_ashr_i32 s8, s3, 31
	s_abs_i32 s3, s3
	v_rcp_iflag_f32_e32 v98, v98
	s_nop 0
	v_mul_f32_e32 v98, 0x4f7ffffe, v98
	v_cvt_u32_f32_e32 v98, v98
	s_nop 0
	v_readfirstlane_b32 s10, v98
	s_mul_i32 s9, s9, s10
	s_mul_hi_u32 s9, s10, s9
	s_add_i32 s10, s10, s9
	s_mul_hi_u32 s9, s3, s10
	s_mul_i32 s9, s9, s5
	s_sub_i32 s3, s3, s9
	s_sub_i32 s9, s3, s5
	s_cmp_ge_u32 s3, s5
	s_cselect_b32 s3, s9, s3
	s_sub_i32 s9, s3, s5
	s_cmp_ge_u32 s3, s5
	s_cselect_b32 s3, s9, s3
	s_xor_b32 s3, s3, s8
	s_sub_i32 s3, s3, s8
	s_add_i32 s4, s4, s3
	v_lshl_add_u32 v98, s4, 8, v0
	v_ashrrev_i32_e32 v99, 31, v98
	v_lshlrev_b64 v[98:99], 6, v[98:99]
	v_lshl_add_u64 v[110:111], s[0:1], 0, v[98:99]
	global_load_dwordx4 v[98:101], v[110:111], off offset:48
	global_load_dwordx4 v[102:105], v[110:111], off offset:32
	global_load_dwordx4 v[106:109], v[110:111], off offset:16
	s_nop 0
	global_load_dwordx4 v[110:113], v[110:111], off
.Lprs5_w:
	s_waitcnt vmcnt(0)
	s_and_b64 vcc, exec, s[44:45]
	s_cbranch_vccnz .Lprs5_c1
	s_mov_b32 s3, 0x800000
	s_waitcnt vmcnt(2)
	v_add_f32_e32 v30, v30, v31
	v_add_f32_e32 v32, v32, v33
	s_waitcnt vmcnt(0)
	v_mov_b32_e32 v42, v39
	v_mov_b32_e32 v43, v40
	v_mov_b32_e32 v39, v41
	v_mov_b32_e32 v40, v35
	v_mov_b32_e32 v41, v36
	v_mov_b32_e32 v35, v37
	v_pk_add_f32 v[38:39], v[42:43], v[38:39]
	v_pk_add_f32 v[34:35], v[40:41], v[34:35]
	v_pk_add_f32 v[38:39], v[38:39], v[38:39] op_sel:[0,1] op_sel_hi:[1,0]
	v_pk_add_f32 v[34:35], v[34:35], v[34:35] op_sel:[0,1] op_sel_hi:[1,0]
	v_mov_b32_e32 v39, v26
	v_mov_b32_e32 v35, v27
	v_mov_b32_e32 v31, v28
	v_mov_b32_e32 v33, v29
	v_pk_add_f32 v[26:27], v[38:39], v[34:35]
	v_pk_add_f32 v[28:29], v[30:31], v[32:33]
	s_nop 0
	v_pk_add_f32 v[26:27], v[26:27], v[28:29]
	s_nop 0
	v_add_f32_e32 v26, v26, v27
	v_mov_b32_e32 v27, 0x358637bd
	v_fmac_f32_e32 v27, 0x3a800000, v26
	v_cmp_gt_f32_e32 vcc, s3, v27
	v_mul_f32_e32 v26, 0x4b800000, v27
	s_nop 0
	v_cndmask_b32_e32 v26, v27, v26, vcc
	v_rsq_f32_e32 v26, v26
	s_nop 0
	v_mul_f32_e32 v27, 0x45800000, v26
	v_cndmask_b32_e32 v26, v26, v27, vcc
	ds_write_b32 v1, v26
.Lprs5_c1:
	v_readlane_b32 s4, v240, 43
	v_mov_b64_e32 v[2:3], 0x2ff
	v_readlane_b32 s5, v240, 44
	s_nop 1
	v_cmp_gt_i64_e32 vcc, s[4:5], v[2:3]
	s_cbranch_vccnz .Lprs5_c2
	s_mov_b32 s3, 0x800000
	s_waitcnt vmcnt(2)
	v_add_f32_e32 v56, v56, v57
	v_add_f32_e32 v58, v58, v59
	s_waitcnt vmcnt(0)
	v_mov_b32_e32 v68, v65
	v_mov_b32_e32 v69, v66
	v_mov_b32_e32 v65, v67
	v_mov_b32_e32 v66, v61
	v_mov_b32_e32 v67, v62
	v_mov_b32_e32 v61, v63
	v_pk_add_f32 v[64:65], v[68:69], v[64:65]
	v_pk_add_f32 v[60:61], v[66:67], v[60:61]
	v_pk_add_f32 v[64:65], v[64:65], v[64:65] op_sel:[0,1] op_sel_hi:[1,0]
	v_pk_add_f32 v[60:61], v[60:61], v[60:61] op_sel:[0,1] op_sel_hi:[1,0]
	v_mov_b32_e32 v65, v52
	v_mov_b32_e32 v61, v53
	v_mov_b32_e32 v57, v54
	v_mov_b32_e32 v59, v55
	v_pk_add_f32 v[52:53], v[64:65], v[60:61]
	v_pk_add_f32 v[54:55], v[56:57], v[58:59]
	s_nop 0
	v_pk_add_f32 v[52:53], v[52:53], v[54:55]
	s_nop 0
	v_add_f32_e32 v52, v52, v53
	v_mov_b32_e32 v53, 0x358637bd
	v_fmac_f32_e32 v53, 0x3a800000, v52
	v_cmp_gt_f32_e32 vcc, s3, v53
	v_mul_f32_e32 v52, 0x4b800000, v53
	s_nop 0
	v_cndmask_b32_e32 v52, v53, v52, vcc
	v_rsq_f32_e32 v52, v52
	s_nop 0
	v_mul_f32_e32 v53, 0x45800000, v52
	v_cndmask_b32_e32 v52, v52, v53, vcc
	ds_write_b32 v1, v52 offset:1024
.Lprs5_c2:
	v_readlane_b32 s4, v240, 53
	v_readlane_b32 s5, v240, 54
	s_nop 1
	v_cmp_gt_i64_e32 vcc, s[4:5], v[2:3]
	s_cbranch_vccnz .Lprs5_c3
	s_mov_b32 s3, 0x800000
	s_waitcnt vmcnt(2)
	v_add_f32_e32 v78, v78, v79
	v_add_f32_e32 v80, v80, v81
	s_waitcnt vmcnt(0)
	v_mov_b32_e32 v90, v87
	v_mov_b32_e32 v91, v88
	v_mov_b32_e32 v87, v89
	v_mov_b32_e32 v88, v83
	v_mov_b32_e32 v89, v84
	v_mov_b32_e32 v83, v85
	v_pk_add_f32 v[86:87], v[90:91], v[86:87]
	v_pk_add_f32 v[82:83], v[88:89], v[82:83]
	v_pk_add_f32 v[86:87], v[86:87], v[86:87] op_sel:[0,1] op_sel_hi:[1,0]
	v_pk_add_f32 v[82:83], v[82:83], v[82:83] op_sel:[0,1] op_sel_hi:[1,0]
	v_mov_b32_e32 v87, v74
	v_mov_b32_e32 v83, v75
	v_mov_b32_e32 v79, v76
	v_mov_b32_e32 v81, v77
	v_pk_add_f32 v[74:75], v[86:87], v[82:83]
	v_pk_add_f32 v[76:77], v[78:79], v[80:81]
	s_nop 0
	v_pk_add_f32 v[74:75], v[74:75], v[76:77]
	s_nop 0
	v_add_f32_e32 v74, v74, v75
	v_mov_b32_e32 v75, 0x358637bd
	v_fmac_f32_e32 v75, 0x3a800000, v74
	v_cmp_gt_f32_e32 vcc, s3, v75
	v_mul_f32_e32 v74, 0x4b800000, v75
	s_nop 0
	v_cndmask_b32_e32 v74, v75, v74, vcc
	v_rsq_f32_e32 v74, v74
	s_nop 0
	v_mul_f32_e32 v75, 0x45800000, v74
	v_cndmask_b32_e32 v74, v74, v75, vcc
	ds_write_b32 v1, v74 offset:2048
.Lprs5_c3:
	v_readlane_b32 s4, v240, 58
	v_mov_b64_e32 v[2:3], 0x2ff
	v_readlane_b32 s5, v240, 59
	s_nop 1
	v_cmp_gt_i64_e32 vcc, s[4:5], v[2:3]
	s_cbranch_vccnz .LBB0_929
	s_mov_b32 s0, 0x800000
	s_waitcnt vmcnt(2)
	v_add_f32_e32 v102, v102, v103
	v_add_f32_e32 v104, v104, v105
	s_waitcnt vmcnt(0)
	v_mov_b32_e32 v114, v111
	v_mov_b32_e32 v115, v112
	v_mov_b32_e32 v111, v113
	v_mov_b32_e32 v112, v107
	v_mov_b32_e32 v113, v108
	v_mov_b32_e32 v107, v109
	v_pk_add_f32 v[110:111], v[114:115], v[110:111]
	v_pk_add_f32 v[106:107], v[112:113], v[106:107]
	v_pk_add_f32 v[110:111], v[110:111], v[110:111] op_sel:[0,1] op_sel_hi:[1,0]
	v_pk_add_f32 v[106:107], v[106:107], v[106:107] op_sel:[0,1] op_sel_hi:[1,0]
	v_mov_b32_e32 v111, v98
	v_mov_b32_e32 v107, v99
	v_mov_b32_e32 v103, v100
	v_mov_b32_e32 v105, v101
	v_pk_add_f32 v[98:99], v[110:111], v[106:107]
	v_pk_add_f32 v[100:101], v[102:103], v[104:105]
	s_nop 0
	v_pk_add_f32 v[98:99], v[98:99], v[100:101]
	s_nop 0
	v_add_f32_e32 v0, v98, v99
	v_mov_b32_e32 v98, 0x358637bd
	v_fmac_f32_e32 v98, 0x3a800000, v0
	v_cmp_gt_f32_e32 vcc, s0, v98
	v_mul_f32_e32 v0, 0x4b800000, v98
	s_nop 0
	v_cndmask_b32_e32 v0, v98, v0, vcc
	v_rsq_f32_e32 v0, v0
	s_nop 0
	v_mul_f32_e32 v98, 0x45800000, v0
	v_cndmask_b32_e32 v0, v0, v98, vcc
	ds_write_b32 v1, v0 offset:3072
